# MLA up-projection epilogue: per-row ssq partial-sum loads batched at the top (3 round trips instead of 8-16 per unit)
# speedup vs baseline: 1.0038x; 1.0017x over previous
;     __device__ __forceinline__ void operator()(const f32x4 (&acc)[2][2][4][2], const Unit& u, int wr_in, int wc_in, int fr_in, int fq_in) const {
;     ...
;             for (int m = 0; m < 4; ++m) {
;                 const int row = u.pm * 256 + ai * 128 + wr * 64 + 4 * fr + m;
;                 const float* sp = ssq + (size_t)row * 20;
;                 const f32x4 p0 = *(const f32x4*)(sp), p1 = *(const f32x4*)(sp + 4);
;                 float ss = (p0[0] + p0[1]) + (p0[2] + p0[3]) + (p1[0] + p1[1]) + (p1[2] + p1[3]);
;                 if (nslot == 12) { const f32x4 p2 = *(const f32x4*)(sp + 8); ss += (p2[0] + p2[1]) + (p2[2] + p2[3]); }
;                 const float rs = sc / sqrtf(ss * invn + RMS_EPS);
.LBB0_190:
	v_mov_b32_e32 v162, v155
	s_mov_b32 s13, s63
	v_mov_b32_e32 v0, v156
	s_mov_b32 s0, s59
	s_lshl_b32 s1, s12, 8
	s_lshl_b32 s0, s0, 6
	v_lshlrev_b32_e32 v0, 2, v0
	s_add_i32 s0, s0, s1
	v_add_u32_e32 v160, s0, v0
	v_mov_b64_e32 v[142:143], s[86:87]
	v_mad_i64_i32 v[144:145], s[0:1], v160, s26, v[142:143]
	s_mov_b64 s[16:17], 0x2800
	v_lshl_add_u64 v[182:183], s[16:17], 0, v[144:145]
	global_load_dwordx4 v[184:187], v[144:145], off
	global_load_dwordx4 v[188:191], v[144:145], off offset:16
	global_load_dwordx4 v[192:195], v[144:145], off offset:32
	global_load_dwordx4 v[196:199], v[144:145], off offset:80
	global_load_dwordx4 v[200:203], v[144:145], off offset:96
	global_load_dwordx4 v[204:207], v[144:145], off offset:112
	global_load_dwordx4 v[208:211], v[144:145], off offset:160
	global_load_dwordx4 v[212:215], v[144:145], off offset:176
	global_load_dwordx4 v[216:219], v[144:145], off offset:192
	s_waitcnt vmcnt(0)
	v_add_f32_e32 v184, v184, v185
	v_add_f32_e32 v186, v186, v187
	v_add_f32_e32 v184, v184, v186
	v_add_f32_e32 v188, v188, v189
	v_add_f32_e32 v184, v184, v188
	v_add_f32_e32 v190, v190, v191
	v_add_f32_e32 v220, v184, v190
	v_add_f32_e32 v192, v192, v193
	v_add_f32_e32 v194, v194, v195
	v_add_f32_e32 v192, v192, v194
	v_cndmask_b32_e64 v192, 0, v192, s[6:7]
	v_add_f32_e32 v220, v220, v192
	v_add_f32_e32 v196, v196, v197
	v_add_f32_e32 v198, v198, v199
	v_add_f32_e32 v196, v196, v198
	v_add_f32_e32 v200, v200, v201
	v_add_f32_e32 v196, v196, v200
	v_add_f32_e32 v202, v202, v203
	v_add_f32_e32 v221, v196, v202
	v_add_f32_e32 v204, v204, v205
	v_add_f32_e32 v206, v206, v207
	v_add_f32_e32 v204, v204, v206
	v_cndmask_b32_e64 v204, 0, v204, s[6:7]
	v_add_f32_e32 v221, v221, v204
	v_add_f32_e32 v208, v208, v209
	v_add_f32_e32 v210, v210, v211
	v_add_f32_e32 v208, v208, v210
	v_add_f32_e32 v212, v212, v213
	v_add_f32_e32 v208, v208, v212
	v_add_f32_e32 v214, v214, v215
	v_add_f32_e32 v222, v208, v214
	v_add_f32_e32 v216, v216, v217
	v_add_f32_e32 v218, v218, v219
	v_add_f32_e32 v216, v216, v218
	v_cndmask_b32_e64 v216, 0, v216, s[6:7]
	v_add_f32_e32 v222, v222, v216
	global_load_dwordx4 v[184:187], v[144:145], off offset:240
	global_load_dwordx4 v[188:191], v[144:145], off offset:256
	global_load_dwordx4 v[192:195], v[144:145], off offset:272
	global_load_dwordx4 v[196:199], v[182:183], off
	global_load_dwordx4 v[200:203], v[182:183], off offset:16
	global_load_dwordx4 v[204:207], v[182:183], off offset:32
	global_load_dwordx4 v[208:211], v[182:183], off offset:80
	global_load_dwordx4 v[212:215], v[182:183], off offset:96
	global_load_dwordx4 v[216:219], v[182:183], off offset:112
	s_waitcnt vmcnt(0)
	v_add_f32_e32 v184, v184, v185
	v_add_f32_e32 v186, v186, v187
	v_add_f32_e32 v184, v184, v186
	v_add_f32_e32 v188, v188, v189
	v_add_f32_e32 v184, v184, v188
	v_add_f32_e32 v190, v190, v191
	v_add_f32_e32 v223, v184, v190
	v_add_f32_e32 v192, v192, v193
	v_add_f32_e32 v194, v194, v195
	v_add_f32_e32 v192, v192, v194
	v_cndmask_b32_e64 v192, 0, v192, s[6:7]
	v_add_f32_e32 v223, v223, v192
	v_add_f32_e32 v196, v196, v197
	v_add_f32_e32 v198, v198, v199
	v_add_f32_e32 v196, v196, v198
	v_add_f32_e32 v200, v200, v201
	v_add_f32_e32 v196, v196, v200
	v_add_f32_e32 v202, v202, v203
	v_add_f32_e32 v224, v196, v202
	v_add_f32_e32 v204, v204, v205
	v_add_f32_e32 v206, v206, v207
	v_add_f32_e32 v204, v204, v206
	v_cndmask_b32_e64 v204, 0, v204, s[6:7]
	v_add_f32_e32 v224, v224, v204
	v_add_f32_e32 v208, v208, v209
	v_add_f32_e32 v210, v210, v211
	v_add_f32_e32 v208, v208, v210
	v_add_f32_e32 v212, v212, v213
	v_add_f32_e32 v208, v208, v212
	v_add_f32_e32 v214, v214, v215
	v_add_f32_e32 v225, v208, v214
	v_add_f32_e32 v216, v216, v217
	v_add_f32_e32 v218, v218, v219
	v_add_f32_e32 v216, v216, v218
	v_cndmask_b32_e64 v216, 0, v216, s[6:7]
	v_add_f32_e32 v225, v225, v216
	global_load_dwordx4 v[184:187], v[182:183], off offset:160
	global_load_dwordx4 v[188:191], v[182:183], off offset:176
	global_load_dwordx4 v[192:195], v[182:183], off offset:192
	global_load_dwordx4 v[196:199], v[182:183], off offset:240
	global_load_dwordx4 v[200:203], v[182:183], off offset:256
	global_load_dwordx4 v[204:207], v[182:183], off offset:272
	s_waitcnt vmcnt(0)
	v_add_f32_e32 v184, v184, v185
	v_add_f32_e32 v186, v186, v187
	v_add_f32_e32 v184, v184, v186
	v_add_f32_e32 v188, v188, v189
	v_add_f32_e32 v184, v184, v188
	v_add_f32_e32 v190, v190, v191
	v_add_f32_e32 v226, v184, v190
	v_add_f32_e32 v192, v192, v193
	v_add_f32_e32 v194, v194, v195
	v_add_f32_e32 v192, v192, v194
	v_cndmask_b32_e64 v192, 0, v192, s[6:7]
	v_add_f32_e32 v226, v226, v192
	v_add_f32_e32 v196, v196, v197
	v_add_f32_e32 v198, v198, v199
	v_add_f32_e32 v196, v196, v198
	v_add_f32_e32 v200, v200, v201
	v_add_f32_e32 v196, v196, v200
	v_add_f32_e32 v202, v202, v203
	v_add_f32_e32 v227, v196, v202
	v_add_f32_e32 v204, v204, v205
	v_add_f32_e32 v206, v206, v207
	v_add_f32_e32 v204, v204, v206
	v_cndmask_b32_e64 v204, 0, v204, s[6:7]
	v_add_f32_e32 v227, v227, v204
	s_nop 1
	v_mov_b32_e32 v146, v220
	v_mov_b32_e32 v147, 0
	v_mov_b32_e32 v148, 0
	v_mov_b32_e32 v149, 0
	v_mov_b32_e32 v150, 0
	v_mov_b32_e32 v151, 0
	v_mov_b32_e32 v152, 0
	v_mov_b32_e32 v153, 0
	s_mov_b64 s[48:49], 0
	s_andn2_b64 vcc, exec, s[6:7]
	s_mov_b64 s[0:1], 0
	s_waitcnt lgkmcnt(0)
	v_mov_b32_e32 v142, v147
	v_mov_b32_e32 v143, v148
	v_mov_b32_e32 v147, v149
	v_pk_add_f32 v[142:143], v[142:143], v[146:147]
	v_mov_b32_e32 v146, v152
	v_mov_b32_e32 v147, v150
	v_mov_b32_e32 v150, v153
	v_pk_add_f32 v[142:143], v[142:143], v[142:143] op_sel:[0,1] op_sel_hi:[1,0]
	v_pk_add_f32 v[146:147], v[146:147], v[150:151]
	s_nop 0
	v_pk_add_f32 v[142:143], v[142:143], v[146:147] op_sel:[0,1] op_sel_hi:[1,0]
	s_nop 0
	v_pk_add_f32 v[142:143], v[146:147], v[142:143]
	s_nop 0
	v_cndmask_b32_e64 v143, 0, 1, s[6:7]
	v_cmp_ne_u32_e64 s[42:43], 1, v143
	s_cbranch_vccnz .LBB0_192
	s_nop 1
	v_mov_b32_e32 v144, 0
	v_mov_b32_e32 v145, 0
	v_mov_b32_e32 v146, 0
	v_mov_b32_e32 v147, 0
	s_cmpk_lt_i32 s12, 0x80
	s_cselect_b64 s[0:1], -1, 0
	s_waitcnt lgkmcnt(0)
	v_mov_b32_e32 v148, v145
	v_mov_b32_e32 v149, v146
	v_mov_b32_e32 v145, v147
	v_pk_add_f32 v[144:145], v[148:149], v[144:145]
	s_nop 0
	v_add_f32_e32 v143, v144, v145
	v_add_f32_e32 v142, v142, v143

;     __device__ __forceinline__ void operator()(const f32x4 (&acc)[2][2][4][2], const Unit& u, int wr_in, int wc_in, int fr_in, int fq_in) const {
;     ...
;             for (int m = 0; m < 4; ++m) {
;                 const int row = u.pm * 256 + ai * 128 + wr * 64 + 4 * fr + m;
;                 const float* sp = ssq + (size_t)row * 20;
;                 const f32x4 p0 = *(const f32x4*)(sp), p1 = *(const f32x4*)(sp + 4);
;                 float ss = (p0[0] + p0[1]) + (p0[2] + p0[3]) + (p1[0] + p1[1]) + (p1[2] + p1[3]);
;                 if (nslot == 12) { const f32x4 p2 = *(const f32x4*)(sp + 8); ss += (p2[0] + p2[1]) + (p2[2] + p2[3]); }
;                 const float rs = sc / sqrtf(ss * invn + RMS_EPS);
; #pragma unroll
;                 for (int bj = 0; bj < 2; ++bj) {
;                     const int g32 = u.pn * 8 + bj * 4 + wc;
;                     const int rope = (isq && lat && (g32 % 3 == 2)) ? 1 : 0;
;                     f32x4 v0 = acc[ai][bj][m][0] * rs, v1 = acc[ai][bj][m][1] * rs;
;                     if (rope) rope_apply(v0, v1, 1, row, wc, fq, tabM, tabM);
;                     store_bf16x8(O + (size_t)row * ldo + g32 * 32 + 8 * fq, v0, v1);
.LBB0_200:
	s_lshl_b32 s96, s12, 5
	s_ashr_i32 s97, s96, 31
	v_lshl_add_u64 v[114:115], s[96:97], 1, v[124:125]
	v_lshl_add_u64 v[118:119], v[122:123], 1, v[114:115]
	v_cvt_pk_bf16_f32 v114, v128, v129
	v_cvt_pk_bf16_f32 v115, v126, v127
	v_cvt_pk_bf16_f32 v116, v144, v145
	v_cvt_pk_bf16_f32 v117, v146, v147
	flat_store_dwordx4 v[118:119], v[114:117]
	v_or_b32_e32 v126, 1, v160
	s_and_b64 vcc, exec, s[42:43]
	v_mov_b64_e32 v[114:115], s[86:87]
	v_mad_i64_i32 v[114:115], s[0:1], v126, s26, v[114:115]
	s_nop 1
	v_mov_b32_e32 v116, v221
	v_mov_b32_e32 v117, 0
	v_mov_b32_e32 v118, 0
	v_mov_b32_e32 v119, 0
	v_mov_b32_e32 v144, 0
	v_mov_b32_e32 v145, 0
	v_mov_b32_e32 v146, 0
	v_mov_b32_e32 v147, 0
	s_waitcnt lgkmcnt(0)
	v_mov_b32_e32 v120, v117
	v_mov_b32_e32 v121, v118
	v_mov_b32_e32 v117, v119
	v_pk_add_f32 v[116:117], v[120:121], v[116:117]
	v_mov_b32_e32 v118, v146
	v_mov_b32_e32 v119, v144
	v_mov_b32_e32 v144, v147
	v_pk_add_f32 v[116:117], v[116:117], v[116:117] op_sel:[0,1] op_sel_hi:[1,0]
	v_pk_add_f32 v[118:119], v[118:119], v[144:145]
	s_nop 0
	v_pk_add_f32 v[116:117], v[116:117], v[118:119] op_sel:[0,1] op_sel_hi:[1,0]
	s_nop 0
	v_pk_add_f32 v[116:117], v[118:119], v[116:117]
	s_cbranch_vccnz .LBB0_202
	s_nop 1
	v_mov_b32_e32 v118, 0
	v_mov_b32_e32 v119, 0
	v_mov_b32_e32 v120, 0
	v_mov_b32_e32 v121, 0
	s_waitcnt lgkmcnt(0)
	v_mov_b32_e32 v114, v119
	v_mov_b32_e32 v115, v120
	v_mov_b32_e32 v119, v121
	v_pk_add_f32 v[114:115], v[114:115], v[118:119]
	s_nop 0
	v_add_f32_e32 v0, v114, v115
	v_add_f32_e32 v116, v116, v0

;     __device__ __forceinline__ void operator()(const f32x4 (&acc)[2][2][4][2], const Unit& u, int wr_in, int wc_in, int fr_in, int fq_in) const {
;     ...
;             for (int m = 0; m < 4; ++m) {
;                 const int row = u.pm * 256 + ai * 128 + wr * 64 + 4 * fr + m;
;                 const float* sp = ssq + (size_t)row * 20;
;                 const f32x4 p0 = *(const f32x4*)(sp), p1 = *(const f32x4*)(sp + 4);
;                 float ss = (p0[0] + p0[1]) + (p0[2] + p0[3]) + (p1[0] + p1[1]) + (p1[2] + p1[3]);
;                 if (nslot == 12) { const f32x4 p2 = *(const f32x4*)(sp + 8); ss += (p2[0] + p2[1]) + (p2[2] + p2[3]); }
;                 const float rs = sc / sqrtf(ss * invn + RMS_EPS);
; #pragma unroll
;                 for (int bj = 0; bj < 2; ++bj) {
;                     const int g32 = u.pn * 8 + bj * 4 + wc;
;                     const int rope = (isq && lat && (g32 % 3 == 2)) ? 1 : 0;
;                     f32x4 v0 = acc[ai][bj][m][0] * rs, v1 = acc[ai][bj][m][1] * rs;
;                     if (rope) rope_apply(v0, v1, 1, row, wc, fq, tabM, tabM);
;                     store_bf16x8(O + (size_t)row * ldo + g32 * 32 + 8 * fq, v0, v1);
.LBB0_210:
	v_lshl_add_u64 v[98:99], s[96:97], 1, v[106:107]
	v_lshl_add_u64 v[102:103], v[122:123], 1, v[98:99]
	v_cvt_pk_bf16_f32 v98, v110, v111
	v_cvt_pk_bf16_f32 v99, v108, v109
	v_cvt_pk_bf16_f32 v100, v114, v115
	v_cvt_pk_bf16_f32 v101, v112, v113
	flat_store_dwordx4 v[102:103], v[98:101]
	v_or_b32_e32 v108, 2, v160
	s_and_b64 vcc, exec, s[42:43]
	v_mov_b64_e32 v[98:99], s[86:87]
	v_mad_i64_i32 v[98:99], s[0:1], v108, s26, v[98:99]
	s_nop 1
	v_mov_b32_e32 v100, v222
	v_mov_b32_e32 v101, 0
	v_mov_b32_e32 v102, 0
	v_mov_b32_e32 v103, 0
	v_mov_b32_e32 v104, 0
	v_mov_b32_e32 v105, 0
	v_mov_b32_e32 v106, 0
	v_mov_b32_e32 v107, 0
	s_waitcnt lgkmcnt(0)
	v_mov_b32_e32 v110, v101
	v_mov_b32_e32 v111, v102
	v_mov_b32_e32 v101, v103
	v_pk_add_f32 v[100:101], v[110:111], v[100:101]
	v_mov_b32_e32 v102, v106
	v_mov_b32_e32 v103, v104
	v_mov_b32_e32 v104, v107
	v_pk_add_f32 v[100:101], v[100:101], v[100:101] op_sel:[0,1] op_sel_hi:[1,0]
	v_pk_add_f32 v[102:103], v[102:103], v[104:105]
	s_nop 0
	v_pk_add_f32 v[100:101], v[100:101], v[102:103] op_sel:[0,1] op_sel_hi:[1,0]
	s_nop 0
	v_pk_add_f32 v[100:101], v[102:103], v[100:101]
	s_cbranch_vccnz .LBB0_212
	s_nop 1
	v_mov_b32_e32 v102, 0
	v_mov_b32_e32 v103, 0
	v_mov_b32_e32 v104, 0
	v_mov_b32_e32 v105, 0
	s_waitcnt lgkmcnt(0)
	v_mov_b32_e32 v98, v103
	v_mov_b32_e32 v99, v104
	v_mov_b32_e32 v103, v105
	v_pk_add_f32 v[98:99], v[98:99], v[102:103]
	s_nop 0
	v_add_f32_e32 v0, v98, v99
	v_add_f32_e32 v100, v100, v0

;     __device__ __forceinline__ void operator()(const f32x4 (&acc)[2][2][4][2], const Unit& u, int wr_in, int wc_in, int fr_in, int fq_in) const {
;     ...
;             for (int m = 0; m < 4; ++m) {
;                 const int row = u.pm * 256 + ai * 128 + wr * 64 + 4 * fr + m;
;                 const float* sp = ssq + (size_t)row * 20;
;                 const f32x4 p0 = *(const f32x4*)(sp), p1 = *(const f32x4*)(sp + 4);
;                 float ss = (p0[0] + p0[1]) + (p0[2] + p0[3]) + (p1[0] + p1[1]) + (p1[2] + p1[3]);
;                 if (nslot == 12) { const f32x4 p2 = *(const f32x4*)(sp + 8); ss += (p2[0] + p2[1]) + (p2[2] + p2[3]); }
;                 const float rs = sc / sqrtf(ss * invn + RMS_EPS);
; #pragma unroll
;                 for (int bj = 0; bj < 2; ++bj) {
;                     const int g32 = u.pn * 8 + bj * 4 + wc;
;                     const int rope = (isq && lat && (g32 % 3 == 2)) ? 1 : 0;
;                     f32x4 v0 = acc[ai][bj][m][0] * rs, v1 = acc[ai][bj][m][1] * rs;
;                     if (rope) rope_apply(v0, v1, 1, row, wc, fq, tabM, tabM);
;                     store_bf16x8(O + (size_t)row * ldo + g32 * 32 + 8 * fq, v0, v1);
.LBB0_220:
	v_lshl_add_u64 v[82:83], s[96:97], 1, v[90:91]
	v_lshl_add_u64 v[86:87], v[122:123], 1, v[82:83]
	v_cvt_pk_bf16_f32 v82, v94, v95
	v_cvt_pk_bf16_f32 v83, v92, v93
	v_cvt_pk_bf16_f32 v84, v98, v99
	v_cvt_pk_bf16_f32 v85, v96, v97
	flat_store_dwordx4 v[86:87], v[82:85]
	v_or_b32_e32 v92, 3, v160
	s_and_b64 vcc, exec, s[42:43]
	v_mov_b64_e32 v[82:83], s[86:87]
	v_mad_i64_i32 v[82:83], s[0:1], v92, s26, v[82:83]
	s_nop 1
	v_mov_b32_e32 v84, v223
	v_mov_b32_e32 v85, 0
	v_mov_b32_e32 v86, 0
	v_mov_b32_e32 v87, 0
	v_mov_b32_e32 v88, 0
	v_mov_b32_e32 v89, 0
	v_mov_b32_e32 v90, 0
	v_mov_b32_e32 v91, 0
	s_waitcnt lgkmcnt(0)
	v_mov_b32_e32 v94, v85
	v_mov_b32_e32 v95, v86
	v_mov_b32_e32 v85, v87
	v_pk_add_f32 v[84:85], v[94:95], v[84:85]
	v_mov_b32_e32 v86, v90
	v_mov_b32_e32 v87, v88
	v_mov_b32_e32 v88, v91
	v_pk_add_f32 v[84:85], v[84:85], v[84:85] op_sel:[0,1] op_sel_hi:[1,0]
	v_pk_add_f32 v[86:87], v[86:87], v[88:89]
	s_nop 0
	v_pk_add_f32 v[84:85], v[84:85], v[86:87] op_sel:[0,1] op_sel_hi:[1,0]
	s_nop 0
	v_pk_add_f32 v[84:85], v[86:87], v[84:85]
	s_cbranch_vccnz .LBB0_222
	s_nop 1
	v_mov_b32_e32 v86, 0
	v_mov_b32_e32 v87, 0
	v_mov_b32_e32 v88, 0
	v_mov_b32_e32 v89, 0
	s_waitcnt lgkmcnt(0)
	v_mov_b32_e32 v82, v87
	v_mov_b32_e32 v83, v88
	v_mov_b32_e32 v87, v89
	v_pk_add_f32 v[82:83], v[82:83], v[86:87]
	s_nop 0
	v_add_f32_e32 v0, v82, v83
	v_add_f32_e32 v84, v84, v0

;     __device__ __forceinline__ void operator()(const f32x4 (&acc)[2][2][4][2], const Unit& u, int wr_in, int wc_in, int fr_in, int fq_in) const {
;     ...
;             for (int m = 0; m < 4; ++m) {
;                 const int row = u.pm * 256 + ai * 128 + wr * 64 + 4 * fr + m;
;                 const float* sp = ssq + (size_t)row * 20;
;                 const f32x4 p0 = *(const f32x4*)(sp), p1 = *(const f32x4*)(sp + 4);
;                 float ss = (p0[0] + p0[1]) + (p0[2] + p0[3]) + (p1[0] + p1[1]) + (p1[2] + p1[3]);
;                 if (nslot == 12) { const f32x4 p2 = *(const f32x4*)(sp + 8); ss += (p2[0] + p2[1]) + (p2[2] + p2[3]); }
;                 const float rs = sc / sqrtf(ss * invn + RMS_EPS);
; #pragma unroll
;                 for (int bj = 0; bj < 2; ++bj) {
;                     const int g32 = u.pn * 8 + bj * 4 + wc;
;                     const int rope = (isq && lat && (g32 % 3 == 2)) ? 1 : 0;
;                     f32x4 v0 = acc[ai][bj][m][0] * rs, v1 = acc[ai][bj][m][1] * rs;
;                     if (rope) rope_apply(v0, v1, 1, row, wc, fq, tabM, tabM);
;                     store_bf16x8(O + (size_t)row * ldo + g32 * 32 + 8 * fq, v0, v1);
.LBB0_230:
	v_lshl_add_u64 v[66:67], s[96:97], 1, v[74:75]
	v_lshl_add_u64 v[70:71], v[122:123], 1, v[66:67]
	v_cvt_pk_bf16_f32 v66, v78, v79
	v_cvt_pk_bf16_f32 v67, v76, v77
	v_cvt_pk_bf16_f32 v68, v82, v83
	v_cvt_pk_bf16_f32 v69, v80, v81
	flat_store_dwordx4 v[70:71], v[66:69]
	v_add_u32_e32 v77, 0x80, v160
	s_and_b64 vcc, exec, s[42:43]
	v_mov_b64_e32 v[66:67], s[86:87]
	v_mad_i64_i32 v[66:67], s[0:1], v77, s26, v[66:67]
	s_nop 1
	v_mov_b32_e32 v68, v224
	v_mov_b32_e32 v69, 0
	v_mov_b32_e32 v70, 0
	v_mov_b32_e32 v71, 0
	v_mov_b32_e32 v72, 0
	v_mov_b32_e32 v73, 0
	v_mov_b32_e32 v74, 0
	v_mov_b32_e32 v75, 0
	s_waitcnt lgkmcnt(0)
	v_mov_b32_e32 v78, v69
	v_mov_b32_e32 v79, v70
	v_mov_b32_e32 v69, v71
	v_pk_add_f32 v[68:69], v[78:79], v[68:69]
	v_mov_b32_e32 v70, v74
	v_mov_b32_e32 v71, v72
	v_mov_b32_e32 v72, v75
	v_pk_add_f32 v[68:69], v[68:69], v[68:69] op_sel:[0,1] op_sel_hi:[1,0]
	v_pk_add_f32 v[70:71], v[70:71], v[72:73]
	s_nop 0
	v_pk_add_f32 v[68:69], v[68:69], v[70:71] op_sel:[0,1] op_sel_hi:[1,0]
	s_nop 0
	v_pk_add_f32 v[68:69], v[70:71], v[68:69]
	s_cbranch_vccnz .LBB0_232
	s_nop 1
	v_mov_b32_e32 v70, 0
	v_mov_b32_e32 v71, 0
	v_mov_b32_e32 v72, 0
	v_mov_b32_e32 v73, 0
	s_waitcnt lgkmcnt(0)
	v_mov_b32_e32 v66, v71
	v_mov_b32_e32 v67, v72
	v_mov_b32_e32 v71, v73
	v_pk_add_f32 v[66:67], v[66:67], v[70:71]
	s_nop 0
	v_add_f32_e32 v0, v66, v67
	v_add_f32_e32 v68, v68, v0

;     __device__ __forceinline__ void operator()(const f32x4 (&acc)[2][2][4][2], const Unit& u, int wr_in, int wc_in, int fr_in, int fq_in) const {
;     ...
;             for (int m = 0; m < 4; ++m) {
;                 const int row = u.pm * 256 + ai * 128 + wr * 64 + 4 * fr + m;
;                 const float* sp = ssq + (size_t)row * 20;
;                 const f32x4 p0 = *(const f32x4*)(sp), p1 = *(const f32x4*)(sp + 4);
;                 float ss = (p0[0] + p0[1]) + (p0[2] + p0[3]) + (p1[0] + p1[1]) + (p1[2] + p1[3]);
;                 if (nslot == 12) { const f32x4 p2 = *(const f32x4*)(sp + 8); ss += (p2[0] + p2[1]) + (p2[2] + p2[3]); }
;                 const float rs = sc / sqrtf(ss * invn + RMS_EPS);
; #pragma unroll
;                 for (int bj = 0; bj < 2; ++bj) {
;                     const int g32 = u.pn * 8 + bj * 4 + wc;
;                     const int rope = (isq && lat && (g32 % 3 == 2)) ? 1 : 0;
;                     f32x4 v0 = acc[ai][bj][m][0] * rs, v1 = acc[ai][bj][m][1] * rs;
;                     if (rope) rope_apply(v0, v1, 1, row, wc, fq, tabM, tabM);
;                     store_bf16x8(O + (size_t)row * ldo + g32 * 32 + 8 * fq, v0, v1);
.LBB0_240:
	v_lshl_add_u64 v[50:51], s[96:97], 1, v[58:59]
	v_lshl_add_u64 v[54:55], v[122:123], 1, v[50:51]
	v_cvt_pk_bf16_f32 v50, v62, v63
	v_cvt_pk_bf16_f32 v51, v60, v61
	v_cvt_pk_bf16_f32 v52, v66, v67
	v_cvt_pk_bf16_f32 v53, v64, v65
	flat_store_dwordx4 v[54:55], v[50:53]
	v_or_b32_e32 v60, 1, v77
	s_and_b64 vcc, exec, s[42:43]
	v_mov_b64_e32 v[50:51], s[86:87]
	v_mad_i64_i32 v[50:51], s[0:1], v60, s26, v[50:51]
	s_nop 1
	v_mov_b32_e32 v52, v225
	v_mov_b32_e32 v53, 0
	v_mov_b32_e32 v54, 0
	v_mov_b32_e32 v55, 0
	v_mov_b32_e32 v56, 0
	v_mov_b32_e32 v57, 0
	v_mov_b32_e32 v58, 0
	v_mov_b32_e32 v59, 0
	s_waitcnt lgkmcnt(0)
	v_mov_b32_e32 v62, v53
	v_mov_b32_e32 v63, v54
	v_mov_b32_e32 v53, v55
	v_pk_add_f32 v[52:53], v[62:63], v[52:53]
	v_mov_b32_e32 v54, v58
	v_mov_b32_e32 v55, v56
	v_mov_b32_e32 v56, v59
	v_pk_add_f32 v[52:53], v[52:53], v[52:53] op_sel:[0,1] op_sel_hi:[1,0]
	v_pk_add_f32 v[54:55], v[54:55], v[56:57]
	s_nop 0
	v_pk_add_f32 v[52:53], v[52:53], v[54:55] op_sel:[0,1] op_sel_hi:[1,0]
	s_nop 0
	v_pk_add_f32 v[52:53], v[54:55], v[52:53]
	s_cbranch_vccnz .LBB0_242
	s_nop 1
	v_mov_b32_e32 v54, 0
	v_mov_b32_e32 v55, 0
	v_mov_b32_e32 v56, 0
	v_mov_b32_e32 v57, 0
	s_waitcnt lgkmcnt(0)
	v_mov_b32_e32 v50, v55
	v_mov_b32_e32 v51, v56
	v_mov_b32_e32 v55, v57
	v_pk_add_f32 v[50:51], v[50:51], v[54:55]
	s_nop 0
	v_add_f32_e32 v0, v50, v51
	v_add_f32_e32 v52, v52, v0

;     __device__ __forceinline__ void operator()(const f32x4 (&acc)[2][2][4][2], const Unit& u, int wr_in, int wc_in, int fr_in, int fq_in) const {
;     ...
;             for (int m = 0; m < 4; ++m) {
;                 const int row = u.pm * 256 + ai * 128 + wr * 64 + 4 * fr + m;
;                 const float* sp = ssq + (size_t)row * 20;
;                 const f32x4 p0 = *(const f32x4*)(sp), p1 = *(const f32x4*)(sp + 4);
;                 float ss = (p0[0] + p0[1]) + (p0[2] + p0[3]) + (p1[0] + p1[1]) + (p1[2] + p1[3]);
;                 if (nslot == 12) { const f32x4 p2 = *(const f32x4*)(sp + 8); ss += (p2[0] + p2[1]) + (p2[2] + p2[3]); }
;                 const float rs = sc / sqrtf(ss * invn + RMS_EPS);
; #pragma unroll
;                 for (int bj = 0; bj < 2; ++bj) {
;                     const int g32 = u.pn * 8 + bj * 4 + wc;
;                     const int rope = (isq && lat && (g32 % 3 == 2)) ? 1 : 0;
;                     f32x4 v0 = acc[ai][bj][m][0] * rs, v1 = acc[ai][bj][m][1] * rs;
;                     if (rope) rope_apply(v0, v1, 1, row, wc, fq, tabM, tabM);
;                     store_bf16x8(O + (size_t)row * ldo + g32 * 32 + 8 * fq, v0, v1);
.LBB0_250:
	v_lshl_add_u64 v[34:35], s[96:97], 1, v[42:43]
	v_lshl_add_u64 v[38:39], v[122:123], 1, v[34:35]
	v_cvt_pk_bf16_f32 v34, v46, v47
	v_cvt_pk_bf16_f32 v35, v44, v45
	v_cvt_pk_bf16_f32 v36, v50, v51
	v_cvt_pk_bf16_f32 v37, v48, v49
	flat_store_dwordx4 v[38:39], v[34:37]
	v_or_b32_e32 v44, 2, v77
	s_and_b64 vcc, exec, s[42:43]
	v_mov_b64_e32 v[34:35], s[86:87]
	v_mad_i64_i32 v[34:35], s[0:1], v44, s26, v[34:35]
	s_nop 1
	v_mov_b32_e32 v36, v226
	v_mov_b32_e32 v37, 0
	v_mov_b32_e32 v38, 0
	v_mov_b32_e32 v39, 0
	v_mov_b32_e32 v40, 0
	v_mov_b32_e32 v41, 0
	v_mov_b32_e32 v42, 0
	v_mov_b32_e32 v43, 0
	s_waitcnt lgkmcnt(0)
	v_mov_b32_e32 v46, v37
	v_mov_b32_e32 v47, v38
	v_mov_b32_e32 v37, v39
	v_pk_add_f32 v[36:37], v[46:47], v[36:37]
	v_mov_b32_e32 v38, v42
	v_mov_b32_e32 v39, v40
	v_mov_b32_e32 v40, v43
	v_pk_add_f32 v[36:37], v[36:37], v[36:37] op_sel:[0,1] op_sel_hi:[1,0]
	v_pk_add_f32 v[38:39], v[38:39], v[40:41]
	s_nop 0
	v_pk_add_f32 v[36:37], v[36:37], v[38:39] op_sel:[0,1] op_sel_hi:[1,0]
	s_nop 0
	v_pk_add_f32 v[36:37], v[38:39], v[36:37]
	s_cbranch_vccnz .LBB0_252
	s_nop 1
	v_mov_b32_e32 v38, 0
	v_mov_b32_e32 v39, 0
	v_mov_b32_e32 v40, 0
	v_mov_b32_e32 v41, 0
	s_waitcnt lgkmcnt(0)
	v_mov_b32_e32 v34, v39
	v_mov_b32_e32 v35, v40
	v_mov_b32_e32 v39, v41
	v_pk_add_f32 v[34:35], v[34:35], v[38:39]
	s_nop 0
	v_add_f32_e32 v0, v34, v35
	v_add_f32_e32 v36, v36, v0

;     __device__ __forceinline__ void operator()(const f32x4 (&acc)[2][2][4][2], const Unit& u, int wr_in, int wc_in, int fr_in, int fq_in) const {
;     ...
;             for (int m = 0; m < 4; ++m) {
;                 const int row = u.pm * 256 + ai * 128 + wr * 64 + 4 * fr + m;
;                 const float* sp = ssq + (size_t)row * 20;
;                 const f32x4 p0 = *(const f32x4*)(sp), p1 = *(const f32x4*)(sp + 4);
;                 float ss = (p0[0] + p0[1]) + (p0[2] + p0[3]) + (p1[0] + p1[1]) + (p1[2] + p1[3]);
;                 if (nslot == 12) { const f32x4 p2 = *(const f32x4*)(sp + 8); ss += (p2[0] + p2[1]) + (p2[2] + p2[3]); }
;                 const float rs = sc / sqrtf(ss * invn + RMS_EPS);
; #pragma unroll
;                 for (int bj = 0; bj < 2; ++bj) {
;                     const int g32 = u.pn * 8 + bj * 4 + wc;
;                     const int rope = (isq && lat && (g32 % 3 == 2)) ? 1 : 0;
;                     f32x4 v0 = acc[ai][bj][m][0] * rs, v1 = acc[ai][bj][m][1] * rs;
;                     if (rope) rope_apply(v0, v1, 1, row, wc, fq, tabM, tabM);
;                     store_bf16x8(O + (size_t)row * ldo + g32 * 32 + 8 * fq, v0, v1);
.LBB0_260:
	v_lshl_add_u64 v[18:19], s[96:97], 1, v[26:27]
	v_lshl_add_u64 v[22:23], v[122:123], 1, v[18:19]
	v_cvt_pk_bf16_f32 v18, v30, v31
	v_cvt_pk_bf16_f32 v19, v28, v29
	v_cvt_pk_bf16_f32 v20, v34, v35
	v_cvt_pk_bf16_f32 v21, v32, v33
	flat_store_dwordx4 v[22:23], v[18:21]
	v_or_b32_e32 v28, 3, v77
	s_and_b64 vcc, exec, s[42:43]
	v_mov_b64_e32 v[18:19], s[86:87]
	v_mad_i64_i32 v[18:19], s[0:1], v28, s26, v[18:19]
	s_nop 1
	v_mov_b32_e32 v20, v227
	v_mov_b32_e32 v21, 0
	v_mov_b32_e32 v22, 0
	v_mov_b32_e32 v23, 0
	v_mov_b32_e32 v24, 0
	v_mov_b32_e32 v25, 0
	v_mov_b32_e32 v26, 0
	v_mov_b32_e32 v27, 0
	s_waitcnt lgkmcnt(0)
	v_mov_b32_e32 v30, v21
	v_mov_b32_e32 v31, v22
	v_mov_b32_e32 v21, v23
	v_pk_add_f32 v[20:21], v[30:31], v[20:21]
	v_mov_b32_e32 v22, v26
	v_mov_b32_e32 v23, v24
	v_mov_b32_e32 v24, v27
	v_pk_add_f32 v[20:21], v[20:21], v[20:21] op_sel:[0,1] op_sel_hi:[1,0]
	v_pk_add_f32 v[22:23], v[22:23], v[24:25]
	s_nop 0
	v_pk_add_f32 v[20:21], v[20:21], v[22:23] op_sel:[0,1] op_sel_hi:[1,0]
	s_nop 0
	v_pk_add_f32 v[20:21], v[22:23], v[20:21]
	s_cbranch_vccnz .LBB0_262
	s_nop 1
	v_mov_b32_e32 v22, 0
	v_mov_b32_e32 v23, 0
	v_mov_b32_e32 v24, 0
	v_mov_b32_e32 v25, 0
	s_waitcnt lgkmcnt(0)
	v_mov_b32_e32 v18, v23
	v_mov_b32_e32 v19, v24
	v_mov_b32_e32 v23, v25
	v_pk_add_f32 v[18:19], v[18:19], v[22:23]
	s_nop 0
	v_add_f32_e32 v0, v18, v19
	v_add_f32_e32 v20, v20, v0
